# v3 + MLA unit epilogue: gate loads hoisted and issued together, counted vmcnt instead of vmcnt(0) per row group
# speedup vs baseline: 1.0008x; 1.0008x over previous
; __device__ __forceinline__ void mla_attn_phase(LAS unsigned char* lds, const bf16_t* q, const bf16_t* kv, const bf16_t* krope, const bf16_t* projb, bf16_t* y, int unit0, int G, int nu) {
;     ...
;     MLA_EXP(n0, n1);
;     MLA_PV(lds + sl_c + MLA_KB);
;     __syncthreads();
;     const int unit_n = unit + G; const bool more = unit_n < nu;
;     { const int uf_ = more ? unit_n : unit; MLA_FETCH(uf_); }
.LBB0_200:
	v_exp_f32_e32 v48, v48
	v_exp_f32_e32 v65, v32
	v_exp_f32_e32 v32, v49
	v_exp_f32_e32 v49, v33
	v_exp_f32_e32 v33, v50
	v_exp_f32_e32 v50, v34
	v_exp_f32_e32 v34, v51
	v_exp_f32_e32 v51, v35
	v_exp_f32_e32 v35, v52
	v_exp_f32_e32 v52, v36
	v_exp_f32_e32 v36, v53
	v_exp_f32_e32 v53, v37
	v_exp_f32_e32 v37, v54
	v_exp_f32_e32 v54, v38
	v_exp_f32_e32 v38, v55
	v_exp_f32_e32 v39, v39
	v_exp_f32_e32 v55, v56
	v_exp_f32_e32 v56, v40
	v_exp_f32_e32 v40, v57
	v_exp_f32_e32 v57, v41
	s_ashr_i32 s6, s2, 8
	s_ashr_i32 s7, s6, 31
	s_waitcnt vmcnt(2)
	ds_write_b128 v185, v[152:155]
	s_waitcnt vmcnt(1)
	ds_write_b128 v201, v[156:159]
	s_waitcnt vmcnt(0)
	ds_write_b128 v214, v[160:163]
	v_add_f32_e32 v66, v65, v48
	v_add_f32_e32 v68, v50, v33
	v_add_f32_e32 v69, v51, v34
	v_add_f32_e32 v71, v53, v36
	v_cvt_pk_bf16_f32 v33, v33, v34
	v_cvt_pk_bf16_f32 v34, v35, v36
	v_cvt_pk_bf16_f32 v36, v65, v49
	v_add_u32_e32 v65, 0x16000, v233
	s_lshl_b64 s[6:7], s[6:7], 12
	v_add_f32_e32 v67, v49, v32
	v_add_f32_e32 v70, v52, v35
	v_add_f32_e32 v72, v54, v37
	v_add_f32_e32 v73, v39, v38
	v_add_f32_e32 v74, v56, v55
	v_add_f32_e32 v75, v57, v40
	v_cvt_pk_bf16_f32 v32, v48, v32
	v_cvt_pk_bf16_f32 v35, v37, v38
	v_cvt_pk_bf16_f32 v37, v50, v51
	v_cvt_pk_bf16_f32 v38, v52, v53
	v_cvt_pk_bf16_f32 v39, v54, v39
	v_cvt_pk_bf16_f32 v40, v55, v40
	ds_read_b64_tr_b16 v[48:49], v65
	ds_read_b64_tr_b16 v[50:51], v65 offset:1536
	ds_read_b64_tr_b16 v[54:55], v65 offset:1600
	ds_read_b64_tr_b16 v[52:53], v65 offset:64
	s_add_i32 s3, s2, s56
	v_readlane_b32 s16, v254, 47
	v_exp_f32_e32 v41, v58
	v_exp_f32_e32 v58, v42
	v_exp_f32_e32 v42, v59
	v_exp_f32_e32 v59, v43
	v_exp_f32_e32 v43, v60
	v_exp_f32_e32 v60, v44
	v_exp_f32_e32 v44, v61
	v_exp_f32_e32 v61, v45
	s_cmp_lt_i32 s3, s16
	s_cselect_b32 s12, s3, s2
	s_ashr_i32 s8, s12, 8
	v_exp_f32_e32 v45, v62
	v_exp_f32_e32 v62, v46
	v_exp_f32_e32 v46, v63
	v_exp_f32_e32 v47, v47
	s_ashr_i32 s9, s8, 31
	v_add_f32_e32 v76, v58, v41
	v_add_f32_e32 v77, v59, v42
	v_add_f32_e32 v79, v61, v44
	v_cvt_pk_bf16_f32 v41, v41, v42
	v_cvt_pk_bf16_f32 v42, v43, v44
	v_cvt_pk_bf16_f32 v44, v56, v57
	v_add_f32_e32 v56, 0, v66
	s_waitcnt lgkmcnt(0)
	v_mfma_f32_32x32x16_bf16 v[16:31], v[32:35], v[52:55], v[16:31]
	s_lshl_b64 s[10:11], s[8:9], 12
	s_lshl_b32 s8, s12, 8
	v_add_f32_e32 v56, v67, v56
	s_and_b32 s8, s8, 0xf00
	v_add_f32_e32 v56, v68, v56
	s_bfe_u32 s15, s12, 0x40004
	s_or_b32 s12, s10, s8
	v_mfma_f32_32x32x16_bf16 v[0:15], v[32:35], v[48:51], v[0:15]
	s_lshl_b32 s8, s2, 8
	v_add_f32_e32 v78, v60, v43
	v_add_f32_e32 v80, v62, v45
	v_add_f32_e32 v81, v47, v46
	v_cvt_pk_bf16_f32 v43, v45, v46
	v_cvt_pk_bf16_f32 v45, v58, v59
	v_cvt_pk_bf16_f32 v46, v60, v61
	v_add_f32_e32 v60, v69, v56
	ds_read_b64_tr_b16 v[52:53], v65 offset:3072
	ds_read_b64_tr_b16 v[54:55], v65 offset:4608
	ds_read_b64_tr_b16 v[58:59], v65 offset:4672
	ds_read_b64_tr_b16 v[56:57], v65 offset:3136
	s_lshl_b32 s14, s15, 8
	s_and_b32 s8, s8, 0xf00
	s_add_u32 s8, s8, s0
	s_addc_u32 s13, 0, s1
	s_add_u32 s9, s8, s6
	s_addc_u32 s8, s13, s7
	s_mov_b32 s13, s11
	v_add_f32_e32 v60, v70, v60
	s_waitcnt lgkmcnt(0)
	v_mfma_f32_32x32x16_bf16 v[16:31], v[40:43], v[56:59], v[16:31]
	v_lshl_add_u64 v[32:33], s[12:13], 0, v[186:187]
	v_readlane_b32 s12, v254, 17
	v_add_f32_e32 v60, v71, v60
	s_lshl_b32 s2, s2, 3
	v_readlane_b32 s13, v254, 18
	v_add_f32_e32 v60, v72, v60
	s_and_b32 s6, s2, 0x780
	v_mfma_f32_32x32x16_bf16 v[0:15], v[40:43], v[52:55], v[0:15]
	v_mov_b64_e32 v[34:35], s[12:13]
	s_movk_i32 s2, 0xc00
	v_cvt_pk_bf16_f32 v47, v62, v47
	v_add_f32_e32 v66, v73, v60
	ds_read_b64_tr_b16 v[56:57], v65 offset:6144
	ds_read_b64_tr_b16 v[58:59], v65 offset:7680
	ds_read_b64_tr_b16 v[62:63], v65 offset:7744
	ds_read_b64_tr_b16 v[60:61], v65 offset:6208
	v_mad_u64_u32 v[34:35], s[12:13], v32, s2, v[34:35]
	v_mov_b32_e32 v32, v35
	v_add_f32_e32 v66, v74, v66
	v_mad_u64_u32 v[32:33], s[12:13], v33, s2, v[32:33]
	v_add_f32_e32 v66, v75, v66
	v_mov_b32_e32 v35, v32
	s_mul_i32 s76, s15, 0xc0
	v_add_f32_e32 v66, v76, v66
	v_lshl_add_u64 v[32:33], v[34:35], 0, s[76:77]
	v_mov_b32_e32 v201, v179
	v_add_f32_e32 v70, v77, v66
	s_waitcnt lgkmcnt(0)
	v_mfma_f32_32x32x16_bf16 v[16:31], v[36:39], v[60:63], v[16:31]
	v_lshl_add_u64 v[32:33], v[32:33], 0, v[200:201]
	ds_read_b64_tr_b16 v[60:61], v65 offset:9216
	ds_read_b64_tr_b16 v[62:63], v65 offset:10752
	ds_read_b64_tr_b16 v[68:69], v65 offset:10816
	ds_read_b64_tr_b16 v[66:67], v65 offset:9280
	v_add_f32_e32 v65, v78, v70
	s_waitcnt lgkmcnt(0)
	s_barrier
; #define LAS __attribute__((address_space(3)))
; __device__ __forceinline__ int crow(int r, int hi) { return (r & 3) + 8 * (r >> 2) + 4 * hi; }
; __device__ __forceinline__ void mla_attn_phase(LAS unsigned char* lds, const bf16_t* q, const bf16_t* kv, const bf16_t* krope, const bf16_t* projb, bf16_t* y, int unit0, int G, int nu) {
;     ...
;     const int unit_n = unit + G; const bool more = unit_n < nu;
;     { const int uf_ = more ? unit_n : unit; MLA_FETCH(uf_); }
;     lsum += __shfl_xor(lsum, 32);
;     const float inv = 1.0f / lsum;
;     LAS float* stg = (LAS float*)(lds + w * 8704);
; #pragma unroll
;     for (int rr = 0; rr < 16; ++rr) { const int qi = crow(rr, hi); const float a = __shfl(inv, qi); stg[qi * 68 + r32] = o0[rr] * a; stg[qi * 68 + 32 + r32] = o1[rr] * a; }
;     asm volatile("s_waitcnt lgkmcnt(0)" ::: "memory");
	global_load_dwordx4 v[148:151], v[32:33], off
	global_load_dwordx4 v[144:147], v[32:33], off offset:32
	global_load_dwordx4 v[140:143], v[32:33], off offset:64
	global_load_dwordx4 v[136:139], v[32:33], off offset:96
	global_load_dwordx4 v[132:135], v[32:33], off offset:128
	global_load_dwordx4 v[128:131], v[32:33], off offset:160
	v_mfma_f32_32x32x16_bf16 v[0:15], v[36:39], v[56:59], v[0:15]
	v_lshl_add_u64 v[32:33], s[10:11], 0, v[182:183]
	v_readlane_b32 s12, v254, 19
	v_add_f32_e32 v65, v79, v65
	v_lshlrev_b64 v[32:33], 12, v[32:33]
	v_readlane_b32 s13, v254, 20
	v_add_f32_e32 v65, v80, v65
	s_mov_b32 s15, s77
	v_lshl_add_u64 v[32:33], s[12:13], 0, v[32:33]
	v_add_f32_e32 v65, v81, v65
	v_lshl_add_u64 v[32:33], v[32:33], 0, s[14:15]
	v_mov_b32_e32 v203, v179
	v_lshl_add_u64 v[206:207], v[32:33], 0, v[202:203]
	v_add_f32_e32 v56, v64, v65
	v_add_co_u32_e32 v40, vcc, s83, v206
	ds_bpermute_b32 v57, v216, v56
	s_nop 0
	v_addc_co_u32_e32 v41, vcc, 0, v207, vcc
	s_mov_b32 s2, 0x40000
	v_mfma_f32_32x32x16_bf16 v[16:31], v[44:47], v[66:69], v[16:31]
	v_mov_b32_e32 v33, s11
	v_or_b32_e32 v32, s10, v184
	v_lshlrev_b64 v[32:33], 6, v[32:33]
	v_lshl_add_u64 v[208:209], v[188:189], 0, v[32:33]
	s_waitcnt lgkmcnt(0)
	v_add_f32_e32 v58, v56, v57
	v_div_scale_f32 v59, s[10:11], v58, v58, 1.0
	v_mfma_f32_32x32x16_bf16 v[0:15], v[44:47], v[60:63], v[0:15]
	v_add_co_u32_e32 v44, vcc, s2, v206
	s_mov_b32 s2, 0x60000
	s_nop 0
	v_addc_co_u32_e32 v45, vcc, 0, v207, vcc
	v_add_co_u32_e32 v48, vcc, s2, v206
	s_movk_i32 s2, 0x2000
	s_nop 0
	v_addc_co_u32_e32 v49, vcc, 0, v207, vcc
	v_add_co_u32_e32 v60, vcc, s2, v208
	s_mov_b32 s2, 0x80000
	s_nop 0
	v_addc_co_u32_e32 v61, vcc, 0, v209, vcc
	v_rcp_f32_e32 v62, v59
	v_add_co_u32_e32 v52, vcc, s2, v206
	s_mov_b32 s2, 0xa0000
	s_nop 0
	v_addc_co_u32_e32 v53, vcc, 0, v207, vcc
	v_add_co_u32_e32 v56, vcc, s2, v206
	v_fma_f32 v63, -v59, v62, 1.0
	s_nop 0
	v_addc_co_u32_e32 v57, vcc, 0, v207, vcc
	v_fmac_f32_e32 v62, v63, v62
	v_div_scale_f32 v63, vcc, 1.0, v58, 1.0
	v_mul_f32_e32 v64, v63, v62
	v_fma_f32 v65, -v59, v64, v63
	v_fmac_f32_e32 v64, v65, v62
	v_fma_f32 v59, -v59, v64, v63
	v_div_fmas_f32 v59, v59, v62, v64
	v_div_fixup_f32 v68, v59, v58, 1.0
	ds_bpermute_b32 v69, v217, v68
	ds_bpermute_b32 v70, v236, v68
	global_load_dwordx4 v[32:35], v[206:207], off
	global_load_dwordx4 v[36:39], v[208:209], off
	s_nop 0
	global_load_dwordx4 v[40:43], v[40:41], off
	s_nop 0
	global_load_dwordx4 v[44:47], v[44:45], off
	s_waitcnt lgkmcnt(1)
	v_mul_f32_e32 v0, v0, v69
	v_mul_f32_e32 v16, v16, v69
	global_load_dwordx4 v[48:51], v[48:49], off
	s_nop 0
	global_load_dwordx4 v[52:55], v[52:53], off
	s_nop 0
	global_load_dwordx4 v[56:59], v[56:57], off
	s_nop 0
	global_load_dwordx4 v[64:67], v[60:61], off offset:-4096
	s_nop 0
	global_load_dwordx4 v[60:63], v[60:61], off
	ds_write2_b32 v235, v0, v16 offset1:32
	ds_bpermute_b32 v0, v219, v68
	s_waitcnt lgkmcnt(2)
	v_mul_f32_e32 v1, v1, v70
	v_mul_f32_e32 v16, v17, v70
	ds_write2_b32 v237, v1, v16 offset1:32
	ds_bpermute_b32 v1, v220, v68
	s_waitcnt lgkmcnt(2)
	v_mul_f32_e32 v2, v2, v0
	v_mul_f32_e32 v0, v18, v0
	v_add_u32_e32 v16, 0x110, v237
	ds_write2_b32 v16, v2, v0 offset1:32
	ds_bpermute_b32 v0, v221, v68
	s_waitcnt lgkmcnt(2)
	v_mul_f32_e32 v2, v3, v1
	v_mul_f32_e32 v1, v19, v1
	v_add_u32_e32 v3, 0x220, v237
	ds_write2_b32 v3, v2, v1 offset1:32
	ds_bpermute_b32 v1, v222, v68
	s_waitcnt lgkmcnt(2)
	v_mul_f32_e32 v2, v4, v0
	v_mul_f32_e32 v0, v20, v0
	v_add_u32_e32 v3, 0x770, v237
	ds_write2_b32 v3, v2, v0 offset1:32
	ds_bpermute_b32 v0, v223, v68
	s_waitcnt lgkmcnt(2)
	v_mul_f32_e32 v2, v5, v1
	v_mul_f32_e32 v1, v21, v1
	v_add_u32_e32 v3, 0x880, v237
	ds_write2_b32 v3, v2, v1 offset1:32
	ds_bpermute_b32 v1, v224, v68
	s_waitcnt lgkmcnt(2)
	v_mul_f32_e32 v2, v6, v0
	v_mul_f32_e32 v0, v22, v0
	v_add_u32_e32 v3, 0x990, v237
	ds_write2_b32 v3, v2, v0 offset1:32
	ds_bpermute_b32 v0, v225, v68
	s_waitcnt lgkmcnt(2)
	v_mul_f32_e32 v2, v7, v1
	v_mul_f32_e32 v1, v23, v1
	v_add_u32_e32 v3, 0xaa0, v237
	ds_write2_b32 v3, v2, v1 offset1:32
	ds_bpermute_b32 v1, v226, v68
	s_waitcnt lgkmcnt(2)
	v_mul_f32_e32 v2, v8, v0
	v_mul_f32_e32 v0, v24, v0
	v_add_u32_e32 v3, 0xff0, v237
	ds_write2_b32 v3, v2, v0 offset1:32
	ds_bpermute_b32 v0, v227, v68
	s_waitcnt lgkmcnt(2)
	v_mul_f32_e32 v2, v9, v1
	v_mul_f32_e32 v1, v25, v1
	v_add_u32_e32 v3, 0x1100, v237
	ds_write2_b32 v3, v2, v1 offset1:32
	ds_bpermute_b32 v1, v228, v68
	s_waitcnt lgkmcnt(2)
	v_mul_f32_e32 v2, v10, v0
	v_mul_f32_e32 v0, v26, v0
	v_add_u32_e32 v3, 0x1210, v237
	ds_write2_b32 v3, v2, v0 offset1:32
	ds_bpermute_b32 v0, v229, v68
	s_waitcnt lgkmcnt(2)
	v_mul_f32_e32 v2, v11, v1
	v_mul_f32_e32 v1, v27, v1
	v_add_u32_e32 v3, 0x1320, v237
	ds_write2_b32 v3, v2, v1 offset1:32
	ds_bpermute_b32 v1, v230, v68
	s_waitcnt lgkmcnt(2)
	v_mul_f32_e32 v2, v12, v0
	v_mul_f32_e32 v0, v28, v0
	ds_write2_b32 v211, v2, v0 offset1:32
	ds_bpermute_b32 v0, v231, v68
	ds_bpermute_b32 v3, v232, v68
	s_waitcnt lgkmcnt(3)
	v_mul_f32_e32 v2, v13, v1
	v_mul_f32_e32 v1, v29, v1
	ds_write2_b32 v251, v2, v1 offset1:32
	s_waitcnt lgkmcnt(2)
	v_mul_f32_e32 v1, v14, v0
	v_mul_f32_e32 v0, v30, v0
	ds_write2_b32 v244, v1, v0 offset1:32
	s_waitcnt lgkmcnt(2)
	v_mul_f32_e32 v0, v15, v3
	v_mul_f32_e32 v1, v31, v3
	v_or_b32_e32 v16, s9, v190
	v_mov_b64_e32 v[2:3], s[54:55]
	s_movk_i32 s2, 0xe00
	ds_write2_b32 v245, v0, v1 offset1:32
	v_mad_u64_u32 v[0:1], s[10:11], v16, s2, v[2:3]
	v_mov_b32_e32 v28, 0xe00
	s_mov_b32 s7, s77
	v_mad_i32_i24 v1, s8, v28, v1
	v_lshl_add_u64 v[0:1], v[0:1], 0, s[6:7]
	v_mov_b32_e32 v205, v179
	s_waitcnt lgkmcnt(0)
; #define LAS __attribute__((address_space(3)))
; __device__ __forceinline__ unsigned cvtpk(float lo, float hi) { f32x2_t v = {lo, hi}; bf16x2_t b = __builtin_convertvector(v, bf16x2_t); return __builtin_bit_cast(unsigned, b); }
; __device__ __forceinline__ float silu_f(float x) { return x / (1.0f + __expf(-x)); }
; __device__ __forceinline__ void mla_attn_phase(LAS unsigned char* lds, const bf16_t* q, const bf16_t* kv, const bf16_t* krope, const bf16_t* projb, bf16_t* y, int unit0, int G, int nu) {
;     ...
; #pragma unroll
;     for (int i = 0; i < 4; ++i) { const int row = i * 8 + (lane >> 3), c8 = lane & 7; const size_t tok = row0 + qb * 256 + w * 32 + row;
;         const f32x4 x0 = *(const LAS f32x4*)(stg + row * 68 + c8 * 8), x1 = *(const LAS f32x4*)(stg + row * 68 + c8 * 8 + 4);
;         const u32x4 g = *(const u32x4*)(projb + tok * B_INP + 672 + h * 64 + c8 * 8);
;         u32x4 yo; yo.x = cvtpk(x0[0] * silu_f(bf_lo(g.x)), x0[1] * silu_f(bf_hi(g.x))); yo.y = cvtpk(x0[2] * silu_f(bf_lo(g.y)), x0[3] * silu_f(bf_hi(g.y)));
;         yo.z = cvtpk(x1[0] * silu_f(bf_lo(g.z)), x1[1] * silu_f(bf_hi(g.z))); yo.w = cvtpk(x1[2] * silu_f(bf_lo(g.w)), x1[3] * silu_f(bf_hi(g.w)));
;         *(u32x4*)(y + tok * DM + h * 64 + c8 * 8) = yo; }
	v_lshl_add_u64 v[0:1], v[0:1], 0, v[204:205]
	v_or_b32_e32 v102, s9, v194
	v_mad_u64_u32 v[100:101], s[10:11], v102, s2, v[2:3]
	v_mad_i32_i24 v101, s8, v28, v101
	v_lshl_add_u64 v[100:101], v[100:101], 0, s[6:7]
	v_lshl_add_u64 v[100:101], v[100:101], 0, v[204:205]
	v_or_b32_e32 v106, s9, v196
	v_mad_u64_u32 v[104:105], s[10:11], v106, s2, v[2:3]
	v_mad_i32_i24 v105, s8, v28, v105
	v_lshl_add_u64 v[104:105], v[104:105], 0, s[6:7]
	v_lshl_add_u64 v[104:105], v[104:105], 0, v[204:205]
	v_or_b32_e32 v110, s9, v198
	v_mad_u64_u32 v[108:109], s[10:11], v110, s2, v[2:3]
	v_mad_i32_i24 v109, s8, v28, v109
	v_lshl_add_u64 v[108:109], v[108:109], 0, s[6:7]
	v_lshl_add_u64 v[108:109], v[108:109], 0, v[204:205]
	global_load_dwordx4 v[84:87], v[0:1], off offset:1344
	global_load_dwordx4 v[88:91], v[100:101], off offset:1344
	global_load_dwordx4 v[92:95], v[104:105], off offset:1344
	global_load_dwordx4 v[96:99], v[108:109], off offset:1344
	v_mov_b32_e32 v17, s8
	s_cmp_ge_i32 s3, s16
	s_waitcnt vmcnt(3)
	v_mov_b32_e32 v4, v84
	v_mov_b32_e32 v5, v85
	v_mov_b32_e32 v6, v86
	v_mov_b32_e32 v7, v87
	v_lshlrev_b32_e32 v22, 16, v4
	v_and_b32_e32 v4, 0xffff0000, v4
	v_mul_f32_e32 v0, 0xbfb8aa3b, v22
	v_exp_f32_e32 v8, v0
	v_mul_f32_e32 v0, 0xbfb8aa3b, v4
	v_exp_f32_e32 v9, v0
	v_and_b32_e32 v26, 0xffff0000, v5
	v_lshl_add_u64 v[0:1], v[192:193], 0, s[6:7]
	v_pk_add_f32 v[18:19], v[8:9], 1.0 op_sel_hi:[1,0]
	s_nop 0
	v_div_scale_f32 v20, s[10:11], v19, v19, v4
	v_rcp_f32_e32 v21, v20
	ds_read_b128 v[8:11], v250
	ds_read_b128 v[12:15], v250 offset:16
	v_fma_f32 v23, -v20, v21, 1.0
	v_fmac_f32_e32 v21, v23, v21
	v_div_scale_f32 v23, vcc, v4, v19, v4
	v_mul_f32_e32 v24, v23, v21
	v_fma_f32 v25, -v20, v24, v23
	v_fmac_f32_e32 v24, v25, v21
	v_fma_f32 v20, -v20, v24, v23
	v_div_scale_f32 v23, s[10:11], v18, v18, v22
	v_rcp_f32_e32 v25, v23
	v_div_fmas_f32 v20, v20, v21, v24
	v_div_fixup_f32 v19, v20, v19, v4
	v_div_scale_f32 v20, vcc, v22, v18, v22
	v_fma_f32 v4, -v23, v25, 1.0
	v_fmac_f32_e32 v25, v4, v25
	v_mul_f32_e32 v21, v20, v25
	v_fma_f32 v4, -v23, v21, v20
	v_lshlrev_b32_e32 v24, 16, v5
	v_fmac_f32_e32 v21, v4, v25
	v_mul_f32_e32 v4, 0xbfb8aa3b, v24
	v_mul_f32_e32 v5, 0xbfb8aa3b, v26
	v_exp_f32_e32 v4, v4
	v_exp_f32_e32 v5, v5
	v_fma_f32 v20, -v23, v21, v20
	v_div_fmas_f32 v23, v20, v25, v21
	v_div_fixup_f32 v18, v23, v18, v22
	v_pk_add_f32 v[20:21], v[4:5], 1.0 op_sel_hi:[1,0]
	s_waitcnt lgkmcnt(1)
	v_pk_mul_f32 v[4:5], v[8:9], v[18:19]
	v_div_scale_f32 v25, s[10:11], v21, v21, v26
	v_rcp_f32_e32 v27, v25
	v_cvt_pk_bf16_f32 v4, v4, v5
	v_div_scale_f32 v22, s[10:11], v20, v20, v24
	v_fma_f32 v5, -v25, v27, 1.0
	v_fmac_f32_e32 v27, v5, v27
	v_div_scale_f32 v5, vcc, v26, v21, v26
	v_mul_f32_e32 v8, v5, v27
	v_fma_f32 v9, -v25, v8, v5
	v_rcp_f32_e32 v23, v22
	v_fmac_f32_e32 v8, v9, v27
	v_fma_f32 v5, -v25, v8, v5
	v_div_fmas_f32 v5, v5, v27, v8
	v_div_fixup_f32 v9, v5, v21, v26
	v_fma_f32 v5, -v22, v23, 1.0
	v_fmac_f32_e32 v23, v5, v23
	v_div_scale_f32 v5, vcc, v24, v20, v24
	v_mul_f32_e32 v8, v5, v23
	v_fma_f32 v18, -v22, v8, v5
	v_lshlrev_b32_e32 v21, 16, v6
	v_and_b32_e32 v6, 0xffff0000, v6
	v_fmac_f32_e32 v8, v18, v23
	v_mul_f32_e32 v18, 0xbfb8aa3b, v21
	v_mul_f32_e32 v19, 0xbfb8aa3b, v6
	v_exp_f32_e32 v18, v18
	v_exp_f32_e32 v19, v19
	v_fma_f32 v5, -v22, v8, v5
	v_div_fmas_f32 v5, v5, v23, v8
	v_div_fixup_f32 v8, v5, v20, v24
	v_pk_add_f32 v[18:19], v[18:19], 1.0 op_sel_hi:[1,0]
	v_pk_mul_f32 v[8:9], v[10:11], v[8:9]
	v_div_scale_f32 v22, s[10:11], v19, v19, v6
	v_rcp_f32_e32 v23, v22
	v_cvt_pk_bf16_f32 v5, v8, v9
	v_lshlrev_b32_e32 v20, 16, v7
	v_fma_f32 v8, -v22, v23, 1.0
	v_fmac_f32_e32 v23, v8, v23
	v_div_scale_f32 v8, vcc, v6, v19, v6
	v_mul_f32_e32 v9, v8, v23
	v_fma_f32 v10, -v22, v9, v8
	v_fmac_f32_e32 v9, v10, v23
	v_div_scale_f32 v10, s[10:11], v18, v18, v21
	v_rcp_f32_e32 v11, v10
	v_fma_f32 v8, -v22, v9, v8
	v_div_fmas_f32 v8, v8, v23, v9
	v_div_fixup_f32 v9, v8, v19, v6
	v_fma_f32 v6, -v10, v11, 1.0
	v_fmac_f32_e32 v11, v6, v11
	v_div_scale_f32 v8, vcc, v21, v18, v21
	v_mul_f32_e32 v19, v8, v11
	v_fma_f32 v6, -v10, v19, v8
	v_and_b32_e32 v22, 0xffff0000, v7
	v_fmac_f32_e32 v19, v6, v11
	v_mul_f32_e32 v6, 0xbfb8aa3b, v20
	v_mul_f32_e32 v7, 0xbfb8aa3b, v22
	v_exp_f32_e32 v6, v6
	v_exp_f32_e32 v7, v7
	v_fma_f32 v8, -v10, v19, v8
	v_div_fmas_f32 v8, v8, v11, v19
	v_div_fixup_f32 v8, v8, v18, v21
	v_pk_add_f32 v[10:11], v[6:7], 1.0 op_sel_hi:[1,0]
	s_waitcnt lgkmcnt(0)
	v_pk_mul_f32 v[6:7], v[12:13], v[8:9]
	v_div_scale_f32 v19, s[10:11], v11, v11, v22
	v_rcp_f32_e32 v23, v19
	v_cvt_pk_bf16_f32 v6, v6, v7
	v_div_scale_f32 v12, s[10:11], v10, v10, v20
	v_fma_f32 v7, -v19, v23, 1.0
	v_fmac_f32_e32 v23, v7, v23
	v_div_scale_f32 v7, vcc, v22, v11, v22
	v_mul_f32_e32 v8, v7, v23
	v_fma_f32 v9, -v19, v8, v7
	v_rcp_f32_e32 v13, v12
	v_fmac_f32_e32 v8, v9, v23
	v_fma_f32 v7, -v19, v8, v7
	v_div_fmas_f32 v7, v7, v23, v8
	v_div_fixup_f32 v9, v7, v11, v22
	v_fma_f32 v7, -v12, v13, 1.0
	v_fmac_f32_e32 v13, v7, v13
	v_div_scale_f32 v7, vcc, v20, v10, v20
	v_mul_f32_e32 v8, v7, v13
	v_fma_f32 v11, -v12, v8, v7
	v_fmac_f32_e32 v8, v11, v13
	v_fma_f32 v7, -v12, v8, v7
	v_div_fmas_f32 v7, v7, v13, v8
	v_div_fixup_f32 v8, v7, v10, v20
	v_pk_mul_f32 v[8:9], v[14:15], v[8:9]
	s_nop 0
	v_cvt_pk_bf16_f32 v7, v8, v9
	v_lshlrev_b64 v[8:9], 11, v[16:17]
	v_lshl_add_u64 v[8:9], v[0:1], 0, v[8:9]
	v_or_b32_e32 v16, s9, v194
	global_store_dwordx4 v[8:9], v[4:7], off
	s_nop 1
	v_mad_u64_u32 v[4:5], s[10:11], v16, s2, v[2:3]
	v_mad_i32_i24 v5, s8, v28, v5
	v_lshl_add_u64 v[4:5], v[4:5], 0, s[6:7]
	v_lshl_add_u64 v[4:5], v[4:5], 0, v[204:205]
	s_waitcnt vmcnt(3)
; #define LAS __attribute__((address_space(3)))
; __device__ __forceinline__ unsigned cvtpk(float lo, float hi) { f32x2_t v = {lo, hi}; bf16x2_t b = __builtin_convertvector(v, bf16x2_t); return __builtin_bit_cast(unsigned, b); }
; __device__ __forceinline__ float silu_f(float x) { return x / (1.0f + __expf(-x)); }
; __device__ __forceinline__ void mla_attn_phase(LAS unsigned char* lds, const bf16_t* q, const bf16_t* kv, const bf16_t* krope, const bf16_t* projb, bf16_t* y, int unit0, int G, int nu) {
;     ...
; #pragma unroll
;     for (int i = 0; i < 4; ++i) { const int row = i * 8 + (lane >> 3), c8 = lane & 7; const size_t tok = row0 + qb * 256 + w * 32 + row;
;         const f32x4 x0 = *(const LAS f32x4*)(stg + row * 68 + c8 * 8), x1 = *(const LAS f32x4*)(stg + row * 68 + c8 * 8 + 4);
;         const u32x4 g = *(const u32x4*)(projb + tok * B_INP + 672 + h * 64 + c8 * 8);
;         u32x4 yo; yo.x = cvtpk(x0[0] * silu_f(bf_lo(g.x)), x0[1] * silu_f(bf_hi(g.x))); yo.y = cvtpk(x0[2] * silu_f(bf_lo(g.y)), x0[3] * silu_f(bf_hi(g.y)));
;         yo.z = cvtpk(x1[0] * silu_f(bf_lo(g.z)), x1[1] * silu_f(bf_hi(g.z))); yo.w = cvtpk(x1[2] * silu_f(bf_lo(g.w)), x1[3] * silu_f(bf_hi(g.w)));
;         *(u32x4*)(y + tok * DM + h * 64 + c8 * 8) = yo; }
	v_mov_b32_e32 v4, v88
	v_mov_b32_e32 v5, v89
	v_mov_b32_e32 v6, v90
	v_mov_b32_e32 v7, v91
	v_lshlrev_b32_e32 v22, 16, v4
	v_and_b32_e32 v4, 0xffff0000, v4
	v_mul_f32_e32 v8, 0xbfb8aa3b, v22
	v_mul_f32_e32 v9, 0xbfb8aa3b, v4
	v_exp_f32_e32 v8, v8
	v_exp_f32_e32 v9, v9
	v_and_b32_e32 v26, 0xffff0000, v5
	v_pk_add_f32 v[18:19], v[8:9], 1.0 op_sel_hi:[1,0]
	s_nop 0
	v_div_scale_f32 v20, s[10:11], v19, v19, v4
	v_rcp_f32_e32 v21, v20
	ds_read_b128 v[8:11], v250 offset:2176
	ds_read_b128 v[12:15], v250 offset:2192
	v_fma_f32 v23, -v20, v21, 1.0
	v_fmac_f32_e32 v21, v23, v21
	v_div_scale_f32 v23, vcc, v4, v19, v4
	v_mul_f32_e32 v24, v23, v21
	v_fma_f32 v25, -v20, v24, v23
	v_fmac_f32_e32 v24, v25, v21
	v_fma_f32 v20, -v20, v24, v23
	v_div_scale_f32 v23, s[10:11], v18, v18, v22
	v_rcp_f32_e32 v25, v23
	v_div_fmas_f32 v20, v20, v21, v24
	v_div_fixup_f32 v19, v20, v19, v4
	v_div_scale_f32 v20, vcc, v22, v18, v22
	v_fma_f32 v4, -v23, v25, 1.0
	v_fmac_f32_e32 v25, v4, v25
	v_mul_f32_e32 v21, v20, v25
	v_fma_f32 v4, -v23, v21, v20
	v_lshlrev_b32_e32 v24, 16, v5
	v_fmac_f32_e32 v21, v4, v25
	v_mul_f32_e32 v4, 0xbfb8aa3b, v24
	v_mul_f32_e32 v5, 0xbfb8aa3b, v26
	v_exp_f32_e32 v4, v4
	v_exp_f32_e32 v5, v5
	v_fma_f32 v20, -v23, v21, v20
	v_div_fmas_f32 v23, v20, v25, v21
	v_div_fixup_f32 v18, v23, v18, v22
	v_pk_add_f32 v[20:21], v[4:5], 1.0 op_sel_hi:[1,0]
	s_waitcnt lgkmcnt(1)
	v_pk_mul_f32 v[4:5], v[8:9], v[18:19]
	v_div_scale_f32 v25, s[10:11], v21, v21, v26
	v_rcp_f32_e32 v27, v25
	v_cvt_pk_bf16_f32 v4, v4, v5
	v_div_scale_f32 v22, s[10:11], v20, v20, v24
	v_fma_f32 v5, -v25, v27, 1.0
	v_fmac_f32_e32 v27, v5, v27
	v_div_scale_f32 v5, vcc, v26, v21, v26
	v_mul_f32_e32 v8, v5, v27
	v_fma_f32 v9, -v25, v8, v5
	v_rcp_f32_e32 v23, v22
	v_fmac_f32_e32 v8, v9, v27
	v_fma_f32 v5, -v25, v8, v5
	v_div_fmas_f32 v5, v5, v27, v8
	v_div_fixup_f32 v9, v5, v21, v26
	v_fma_f32 v5, -v22, v23, 1.0
	v_fmac_f32_e32 v23, v5, v23
	v_div_scale_f32 v5, vcc, v24, v20, v24
	v_mul_f32_e32 v8, v5, v23
	v_fma_f32 v18, -v22, v8, v5
	v_lshlrev_b32_e32 v21, 16, v6
	v_and_b32_e32 v6, 0xffff0000, v6
	v_fmac_f32_e32 v8, v18, v23
	v_mul_f32_e32 v18, 0xbfb8aa3b, v21
	v_mul_f32_e32 v19, 0xbfb8aa3b, v6
	v_exp_f32_e32 v18, v18
	v_exp_f32_e32 v19, v19
	v_fma_f32 v5, -v22, v8, v5
	v_div_fmas_f32 v5, v5, v23, v8
	v_div_fixup_f32 v8, v5, v20, v24
	v_pk_add_f32 v[18:19], v[18:19], 1.0 op_sel_hi:[1,0]
	v_pk_mul_f32 v[8:9], v[10:11], v[8:9]
	v_div_scale_f32 v22, s[10:11], v19, v19, v6
	v_rcp_f32_e32 v23, v22
	v_cvt_pk_bf16_f32 v5, v8, v9
	v_lshlrev_b32_e32 v20, 16, v7
	v_fma_f32 v8, -v22, v23, 1.0
	v_fmac_f32_e32 v23, v8, v23
	v_div_scale_f32 v8, vcc, v6, v19, v6
	v_mul_f32_e32 v9, v8, v23
	v_fma_f32 v10, -v22, v9, v8
	v_fmac_f32_e32 v9, v10, v23
	v_div_scale_f32 v10, s[10:11], v18, v18, v21
	v_rcp_f32_e32 v11, v10
	v_fma_f32 v8, -v22, v9, v8
	v_div_fmas_f32 v8, v8, v23, v9
	v_div_fixup_f32 v9, v8, v19, v6
	v_fma_f32 v6, -v10, v11, 1.0
	v_fmac_f32_e32 v11, v6, v11
	v_div_scale_f32 v8, vcc, v21, v18, v21
	v_mul_f32_e32 v19, v8, v11
	v_fma_f32 v6, -v10, v19, v8
	v_and_b32_e32 v22, 0xffff0000, v7
	v_fmac_f32_e32 v19, v6, v11
	v_mul_f32_e32 v6, 0xbfb8aa3b, v20
	v_mul_f32_e32 v7, 0xbfb8aa3b, v22
	v_exp_f32_e32 v6, v6
	v_exp_f32_e32 v7, v7
	v_fma_f32 v8, -v10, v19, v8
	v_div_fmas_f32 v8, v8, v11, v19
	v_div_fixup_f32 v8, v8, v18, v21
	v_pk_add_f32 v[10:11], v[6:7], 1.0 op_sel_hi:[1,0]
	s_waitcnt lgkmcnt(0)
	v_pk_mul_f32 v[6:7], v[12:13], v[8:9]
	v_div_scale_f32 v19, s[10:11], v11, v11, v22
	v_rcp_f32_e32 v23, v19
	v_cvt_pk_bf16_f32 v6, v6, v7
	v_div_scale_f32 v12, s[10:11], v10, v10, v20
	v_fma_f32 v7, -v19, v23, 1.0
	v_fmac_f32_e32 v23, v7, v23
	v_div_scale_f32 v7, vcc, v22, v11, v22
	v_mul_f32_e32 v8, v7, v23
	v_fma_f32 v9, -v19, v8, v7
	v_rcp_f32_e32 v13, v12
	v_fmac_f32_e32 v8, v9, v23
	v_fma_f32 v7, -v19, v8, v7
	v_div_fmas_f32 v7, v7, v23, v8
	v_div_fixup_f32 v9, v7, v11, v22
	v_fma_f32 v7, -v12, v13, 1.0
	v_fmac_f32_e32 v13, v7, v13
	v_div_scale_f32 v7, vcc, v20, v10, v20
	v_mul_f32_e32 v8, v7, v13
	v_fma_f32 v11, -v12, v8, v7
	v_fmac_f32_e32 v8, v11, v13
	v_fma_f32 v7, -v12, v8, v7
	v_div_fmas_f32 v7, v7, v13, v8
	v_div_fixup_f32 v8, v7, v10, v20
	v_pk_mul_f32 v[8:9], v[14:15], v[8:9]
	s_nop 0
	v_cvt_pk_bf16_f32 v7, v8, v9
	v_lshlrev_b64 v[8:9], 11, v[16:17]
	v_lshl_add_u64 v[8:9], v[0:1], 0, v[8:9]
	v_or_b32_e32 v16, s9, v196
	global_store_dwordx4 v[8:9], v[4:7], off
	s_nop 1
	v_mad_u64_u32 v[4:5], s[10:11], v16, s2, v[2:3]
	v_mad_i32_i24 v5, s8, v28, v5
	v_lshl_add_u64 v[4:5], v[4:5], 0, s[6:7]
	v_lshl_add_u64 v[4:5], v[4:5], 0, v[204:205]
	s_waitcnt vmcnt(3)
	v_mov_b32_e32 v4, v92
	v_mov_b32_e32 v5, v93
	v_mov_b32_e32 v6, v94
	v_mov_b32_e32 v7, v95
	v_lshlrev_b32_e32 v22, 16, v4
	v_and_b32_e32 v4, 0xffff0000, v4
	v_mul_f32_e32 v8, 0xbfb8aa3b, v22
	v_mul_f32_e32 v9, 0xbfb8aa3b, v4
	v_exp_f32_e32 v8, v8
	v_exp_f32_e32 v9, v9
	v_and_b32_e32 v26, 0xffff0000, v5
	v_pk_add_f32 v[18:19], v[8:9], 1.0 op_sel_hi:[1,0]
	s_nop 0
	v_div_scale_f32 v20, s[10:11], v19, v19, v4
	v_rcp_f32_e32 v21, v20
	ds_read_b128 v[8:11], v250 offset:4352
	ds_read_b128 v[12:15], v250 offset:4368
	v_fma_f32 v23, -v20, v21, 1.0
	v_fmac_f32_e32 v21, v23, v21
	v_div_scale_f32 v23, vcc, v4, v19, v4
	v_mul_f32_e32 v24, v23, v21
	v_fma_f32 v25, -v20, v24, v23
	v_fmac_f32_e32 v24, v25, v21
	v_fma_f32 v20, -v20, v24, v23
	v_div_scale_f32 v23, s[10:11], v18, v18, v22
	v_rcp_f32_e32 v25, v23
	v_div_fmas_f32 v20, v20, v21, v24
	v_div_fixup_f32 v19, v20, v19, v4
	v_div_scale_f32 v20, vcc, v22, v18, v22
	v_fma_f32 v4, -v23, v25, 1.0
	v_fmac_f32_e32 v25, v4, v25
	v_mul_f32_e32 v21, v20, v25
	v_fma_f32 v4, -v23, v21, v20
	v_lshlrev_b32_e32 v24, 16, v5
	v_fmac_f32_e32 v21, v4, v25
	v_mul_f32_e32 v4, 0xbfb8aa3b, v24
	v_mul_f32_e32 v5, 0xbfb8aa3b, v26
	v_exp_f32_e32 v4, v4
	v_exp_f32_e32 v5, v5
	v_fma_f32 v20, -v23, v21, v20
	v_div_fmas_f32 v23, v20, v25, v21
	v_div_fixup_f32 v18, v23, v18, v22
	v_pk_add_f32 v[20:21], v[4:5], 1.0 op_sel_hi:[1,0]
	s_waitcnt lgkmcnt(1)
; #define LAS __attribute__((address_space(3)))
; __device__ __forceinline__ unsigned cvtpk(float lo, float hi) { f32x2_t v = {lo, hi}; bf16x2_t b = __builtin_convertvector(v, bf16x2_t); return __builtin_bit_cast(unsigned, b); }
; __device__ __forceinline__ float silu_f(float x) { return x / (1.0f + __expf(-x)); }
; __device__ __forceinline__ void mla_attn_phase(LAS unsigned char* lds, const bf16_t* q, const bf16_t* kv, const bf16_t* krope, const bf16_t* projb, bf16_t* y, int unit0, int G, int nu) {
;     ...
; #pragma unroll
;     for (int i = 0; i < 4; ++i) { const int row = i * 8 + (lane >> 3), c8 = lane & 7; const size_t tok = row0 + qb * 256 + w * 32 + row;
;         const f32x4 x0 = *(const LAS f32x4*)(stg + row * 68 + c8 * 8), x1 = *(const LAS f32x4*)(stg + row * 68 + c8 * 8 + 4);
;         const u32x4 g = *(const u32x4*)(projb + tok * B_INP + 672 + h * 64 + c8 * 8);
;         u32x4 yo; yo.x = cvtpk(x0[0] * silu_f(bf_lo(g.x)), x0[1] * silu_f(bf_hi(g.x))); yo.y = cvtpk(x0[2] * silu_f(bf_lo(g.y)), x0[3] * silu_f(bf_hi(g.y)));
;         yo.z = cvtpk(x1[0] * silu_f(bf_lo(g.z)), x1[1] * silu_f(bf_hi(g.z))); yo.w = cvtpk(x1[2] * silu_f(bf_lo(g.w)), x1[3] * silu_f(bf_hi(g.w)));
;         *(u32x4*)(y + tok * DM + h * 64 + c8 * 8) = yo; }
	v_pk_mul_f32 v[4:5], v[8:9], v[18:19]
	v_div_scale_f32 v25, s[10:11], v21, v21, v26
	v_rcp_f32_e32 v27, v25
	v_cvt_pk_bf16_f32 v4, v4, v5
	v_div_scale_f32 v22, s[10:11], v20, v20, v24
	v_fma_f32 v5, -v25, v27, 1.0
	v_fmac_f32_e32 v27, v5, v27
	v_div_scale_f32 v5, vcc, v26, v21, v26
	v_mul_f32_e32 v8, v5, v27
	v_fma_f32 v9, -v25, v8, v5
	v_rcp_f32_e32 v23, v22
	v_fmac_f32_e32 v8, v9, v27
	v_fma_f32 v5, -v25, v8, v5
	v_div_fmas_f32 v5, v5, v27, v8
	v_div_fixup_f32 v9, v5, v21, v26
	v_fma_f32 v5, -v22, v23, 1.0
	v_fmac_f32_e32 v23, v5, v23
	v_div_scale_f32 v5, vcc, v24, v20, v24
	v_mul_f32_e32 v8, v5, v23
	v_fma_f32 v18, -v22, v8, v5
	v_lshlrev_b32_e32 v21, 16, v6
	v_and_b32_e32 v6, 0xffff0000, v6
	v_fmac_f32_e32 v8, v18, v23
	v_mul_f32_e32 v18, 0xbfb8aa3b, v21
	v_mul_f32_e32 v19, 0xbfb8aa3b, v6
	v_exp_f32_e32 v18, v18
	v_exp_f32_e32 v19, v19
	v_fma_f32 v5, -v22, v8, v5
	v_div_fmas_f32 v5, v5, v23, v8
	v_div_fixup_f32 v8, v5, v20, v24
	v_pk_add_f32 v[18:19], v[18:19], 1.0 op_sel_hi:[1,0]
	v_pk_mul_f32 v[8:9], v[10:11], v[8:9]
	v_div_scale_f32 v22, s[10:11], v19, v19, v6
	v_rcp_f32_e32 v23, v22
	v_cvt_pk_bf16_f32 v5, v8, v9
	v_lshlrev_b32_e32 v20, 16, v7
	v_fma_f32 v8, -v22, v23, 1.0
	v_fmac_f32_e32 v23, v8, v23
	v_div_scale_f32 v8, vcc, v6, v19, v6
	v_mul_f32_e32 v9, v8, v23
	v_fma_f32 v10, -v22, v9, v8
	v_fmac_f32_e32 v9, v10, v23
	v_div_scale_f32 v10, s[10:11], v18, v18, v21
	v_rcp_f32_e32 v11, v10
	v_fma_f32 v8, -v22, v9, v8
	v_div_fmas_f32 v8, v8, v23, v9
	v_div_fixup_f32 v9, v8, v19, v6
	v_fma_f32 v6, -v10, v11, 1.0
	v_fmac_f32_e32 v11, v6, v11
	v_div_scale_f32 v8, vcc, v21, v18, v21
	v_mul_f32_e32 v19, v8, v11
	v_fma_f32 v6, -v10, v19, v8
	v_and_b32_e32 v22, 0xffff0000, v7
	v_fmac_f32_e32 v19, v6, v11
	v_mul_f32_e32 v6, 0xbfb8aa3b, v20
	v_mul_f32_e32 v7, 0xbfb8aa3b, v22
	v_exp_f32_e32 v6, v6
	v_exp_f32_e32 v7, v7
	v_fma_f32 v8, -v10, v19, v8
	v_div_fmas_f32 v8, v8, v11, v19
	v_div_fixup_f32 v8, v8, v18, v21
	v_pk_add_f32 v[10:11], v[6:7], 1.0 op_sel_hi:[1,0]
	s_waitcnt lgkmcnt(0)
	v_pk_mul_f32 v[6:7], v[12:13], v[8:9]
	v_div_scale_f32 v19, s[10:11], v11, v11, v22
	v_rcp_f32_e32 v23, v19
	v_cvt_pk_bf16_f32 v6, v6, v7
	v_div_scale_f32 v12, s[10:11], v10, v10, v20
	v_fma_f32 v7, -v19, v23, 1.0
	v_fmac_f32_e32 v23, v7, v23
	v_div_scale_f32 v7, vcc, v22, v11, v22
	v_mul_f32_e32 v8, v7, v23
	v_fma_f32 v9, -v19, v8, v7
	v_rcp_f32_e32 v13, v12
	v_fmac_f32_e32 v8, v9, v23
	v_fma_f32 v7, -v19, v8, v7
	v_div_fmas_f32 v7, v7, v23, v8
	v_div_fixup_f32 v9, v7, v11, v22
	v_fma_f32 v7, -v12, v13, 1.0
	v_fmac_f32_e32 v13, v7, v13
	v_div_scale_f32 v7, vcc, v20, v10, v20
	v_mul_f32_e32 v8, v7, v13
	v_fma_f32 v11, -v12, v8, v7
	v_fmac_f32_e32 v8, v11, v13
	v_fma_f32 v7, -v12, v8, v7
	v_div_fmas_f32 v7, v7, v13, v8
	v_div_fixup_f32 v8, v7, v10, v20
	v_pk_mul_f32 v[8:9], v[14:15], v[8:9]
	v_or_b32_e32 v14, s9, v198
	v_mad_u64_u32 v[2:3], s[10:11], v14, s2, v[2:3]
	v_cvt_pk_bf16_f32 v7, v8, v9
	v_lshlrev_b64 v[8:9], 11, v[16:17]
	v_mad_i32_i24 v3, s8, v28, v3
	v_lshl_add_u64 v[8:9], v[0:1], 0, v[8:9]
	v_lshl_add_u64 v[2:3], v[2:3], 0, s[6:7]
	global_store_dwordx4 v[8:9], v[4:7], off
	v_lshl_add_u64 v[2:3], v[2:3], 0, v[204:205]
	v_mov_b32_e32 v15, s8
	s_mov_b32 s2, s3
	s_waitcnt vmcnt(3)
; #define LAS __attribute__((address_space(3)))
; __device__ __forceinline__ unsigned cvtpk(float lo, float hi) { f32x2_t v = {lo, hi}; bf16x2_t b = __builtin_convertvector(v, bf16x2_t); return __builtin_bit_cast(unsigned, b); }
; __device__ __forceinline__ float silu_f(float x) { return x / (1.0f + __expf(-x)); }
; __device__ __forceinline__ void mla_attn_phase(LAS unsigned char* lds, const bf16_t* q, const bf16_t* kv, const bf16_t* krope, const bf16_t* projb, bf16_t* y, int unit0, int G, int nu) {
;     ...
; #pragma unroll
;     for (int i = 0; i < 4; ++i) { const int row = i * 8 + (lane >> 3), c8 = lane & 7; const size_t tok = row0 + qb * 256 + w * 32 + row;
;         const f32x4 x0 = *(const LAS f32x4*)(stg + row * 68 + c8 * 8), x1 = *(const LAS f32x4*)(stg + row * 68 + c8 * 8 + 4);
;         const u32x4 g = *(const u32x4*)(projb + tok * B_INP + 672 + h * 64 + c8 * 8);
;         u32x4 yo; yo.x = cvtpk(x0[0] * silu_f(bf_lo(g.x)), x0[1] * silu_f(bf_hi(g.x))); yo.y = cvtpk(x0[2] * silu_f(bf_lo(g.y)), x0[3] * silu_f(bf_hi(g.y)));
;         yo.z = cvtpk(x1[0] * silu_f(bf_lo(g.z)), x1[1] * silu_f(bf_hi(g.z))); yo.w = cvtpk(x1[2] * silu_f(bf_lo(g.w)), x1[3] * silu_f(bf_hi(g.w)));
;         *(u32x4*)(y + tok * DM + h * 64 + c8 * 8) = yo; }
;     __syncthreads();
;     if (!more) break;
;     unit = unit_n;
	v_mov_b32_e32 v2, v96
	v_mov_b32_e32 v3, v97
	v_mov_b32_e32 v4, v98
	v_mov_b32_e32 v5, v99
	v_lshlrev_b32_e32 v20, 16, v2
	v_and_b32_e32 v2, 0xffff0000, v2
	v_mul_f32_e32 v6, 0xbfb8aa3b, v20
	v_mul_f32_e32 v7, 0xbfb8aa3b, v2
	v_exp_f32_e32 v6, v6
	v_exp_f32_e32 v7, v7
	v_and_b32_e32 v24, 0xffff0000, v3
	v_pk_add_f32 v[16:17], v[6:7], 1.0 op_sel_hi:[1,0]
	s_nop 0
	v_div_scale_f32 v18, s[6:7], v17, v17, v2
	v_rcp_f32_e32 v19, v18
	ds_read_b128 v[6:9], v250 offset:6528
	ds_read_b128 v[10:13], v250 offset:6544
	v_fma_f32 v21, -v18, v19, 1.0
	v_fmac_f32_e32 v19, v21, v19
	v_div_scale_f32 v21, vcc, v2, v17, v2
	v_mul_f32_e32 v22, v21, v19
	v_fma_f32 v23, -v18, v22, v21
	v_fmac_f32_e32 v22, v23, v19
	v_fma_f32 v18, -v18, v22, v21
	v_div_scale_f32 v21, s[6:7], v16, v16, v20
	v_rcp_f32_e32 v23, v21
	v_div_fmas_f32 v18, v18, v19, v22
	v_div_fixup_f32 v17, v18, v17, v2
	v_div_scale_f32 v18, vcc, v20, v16, v20
	v_fma_f32 v2, -v21, v23, 1.0
	v_fmac_f32_e32 v23, v2, v23
	v_mul_f32_e32 v19, v18, v23
	v_fma_f32 v2, -v21, v19, v18
	v_lshlrev_b32_e32 v22, 16, v3
	v_fmac_f32_e32 v19, v2, v23
	v_mul_f32_e32 v2, 0xbfb8aa3b, v22
	v_mul_f32_e32 v3, 0xbfb8aa3b, v24
	v_exp_f32_e32 v2, v2
	v_exp_f32_e32 v3, v3
	v_fma_f32 v18, -v21, v19, v18
	v_div_fmas_f32 v21, v18, v23, v19
	v_div_fixup_f32 v16, v21, v16, v20
	v_pk_add_f32 v[18:19], v[2:3], 1.0 op_sel_hi:[1,0]
	s_waitcnt lgkmcnt(1)
	v_pk_mul_f32 v[2:3], v[6:7], v[16:17]
	v_div_scale_f32 v23, s[6:7], v19, v19, v24
	v_rcp_f32_e32 v25, v23
	v_cvt_pk_bf16_f32 v2, v2, v3
	v_div_scale_f32 v20, s[6:7], v18, v18, v22
	v_fma_f32 v3, -v23, v25, 1.0
	v_fmac_f32_e32 v25, v3, v25
	v_div_scale_f32 v3, vcc, v24, v19, v24
	v_mul_f32_e32 v6, v3, v25
	v_fma_f32 v7, -v23, v6, v3
	v_rcp_f32_e32 v21, v20
	v_fmac_f32_e32 v6, v7, v25
	v_fma_f32 v3, -v23, v6, v3
	v_div_fmas_f32 v3, v3, v25, v6
	v_div_fixup_f32 v7, v3, v19, v24
	v_fma_f32 v3, -v20, v21, 1.0
	v_fmac_f32_e32 v21, v3, v21
	v_div_scale_f32 v3, vcc, v22, v18, v22
	v_mul_f32_e32 v6, v3, v21
	v_fma_f32 v16, -v20, v6, v3
	v_lshlrev_b32_e32 v19, 16, v4
	v_and_b32_e32 v4, 0xffff0000, v4
	v_fmac_f32_e32 v6, v16, v21
	v_mul_f32_e32 v16, 0xbfb8aa3b, v19
	v_mul_f32_e32 v17, 0xbfb8aa3b, v4
	v_exp_f32_e32 v16, v16
	v_exp_f32_e32 v17, v17
	v_fma_f32 v3, -v20, v6, v3
	v_div_fmas_f32 v3, v3, v21, v6
	v_div_fixup_f32 v6, v3, v18, v22
	v_pk_add_f32 v[16:17], v[16:17], 1.0 op_sel_hi:[1,0]
	v_pk_mul_f32 v[6:7], v[8:9], v[6:7]
	v_div_scale_f32 v20, s[6:7], v17, v17, v4
	v_rcp_f32_e32 v21, v20
	v_cvt_pk_bf16_f32 v3, v6, v7
	v_lshlrev_b32_e32 v18, 16, v5
	v_fma_f32 v6, -v20, v21, 1.0
	v_fmac_f32_e32 v21, v6, v21
	v_div_scale_f32 v6, vcc, v4, v17, v4
	v_mul_f32_e32 v7, v6, v21
	v_fma_f32 v8, -v20, v7, v6
	v_fmac_f32_e32 v7, v8, v21
	v_div_scale_f32 v8, s[6:7], v16, v16, v19
	v_rcp_f32_e32 v9, v8
	v_fma_f32 v6, -v20, v7, v6
	v_div_fmas_f32 v6, v6, v21, v7
	v_div_fixup_f32 v7, v6, v17, v4
	v_fma_f32 v4, -v8, v9, 1.0
	v_fmac_f32_e32 v9, v4, v9
	v_div_scale_f32 v6, vcc, v19, v16, v19
	v_mul_f32_e32 v17, v6, v9
	v_fma_f32 v4, -v8, v17, v6
	v_and_b32_e32 v20, 0xffff0000, v5
	v_fmac_f32_e32 v17, v4, v9
	v_mul_f32_e32 v4, 0xbfb8aa3b, v18
	v_mul_f32_e32 v5, 0xbfb8aa3b, v20
	v_exp_f32_e32 v4, v4
	v_exp_f32_e32 v5, v5
	v_fma_f32 v6, -v8, v17, v6
	v_div_fmas_f32 v6, v6, v9, v17
	v_div_fixup_f32 v6, v6, v16, v19
	v_pk_add_f32 v[8:9], v[4:5], 1.0 op_sel_hi:[1,0]
	s_waitcnt lgkmcnt(0)
	v_pk_mul_f32 v[4:5], v[10:11], v[6:7]
	v_div_scale_f32 v17, s[6:7], v9, v9, v20
	v_rcp_f32_e32 v21, v17
	v_cvt_pk_bf16_f32 v4, v4, v5
	v_div_scale_f32 v10, s[6:7], v8, v8, v18
	v_fma_f32 v5, -v17, v21, 1.0
	v_fmac_f32_e32 v21, v5, v21
	v_div_scale_f32 v5, vcc, v20, v9, v20
	v_mul_f32_e32 v6, v5, v21
	v_fma_f32 v7, -v17, v6, v5
	v_rcp_f32_e32 v11, v10
	v_fmac_f32_e32 v6, v7, v21
	v_fma_f32 v5, -v17, v6, v5
	v_div_fmas_f32 v5, v5, v21, v6
	v_div_fixup_f32 v7, v5, v9, v20
	v_fma_f32 v5, -v10, v11, 1.0
	v_fmac_f32_e32 v11, v5, v11
	v_div_scale_f32 v5, vcc, v18, v8, v18
	v_mul_f32_e32 v6, v5, v11
	v_fma_f32 v9, -v10, v6, v5
	v_fmac_f32_e32 v6, v9, v11
	v_fma_f32 v5, -v10, v6, v5
	v_div_fmas_f32 v5, v5, v11, v6
	v_div_fixup_f32 v6, v5, v8, v18
	v_pk_mul_f32 v[6:7], v[12:13], v[6:7]
	s_nop 0
	v_cvt_pk_bf16_f32 v5, v6, v7
	v_lshlrev_b64 v[6:7], 11, v[14:15]
	v_lshl_add_u64 v[0:1], v[0:1], 0, v[6:7]
	global_store_dwordx4 v[0:1], v[2:5], off
	s_barrier
	s_cbranch_scc1 .LBB0_211
